# v11 + GEMM3 epilogue: per-row rstd cached across consecutive tiles of the same row panel (same as the GEMM8 cache)
# baseline (speedup 1.0000x reference)
;     __host__ __device__ bool next(int i, Unit& u) const {
;         const long L = (long)i * G + c; if (L >= nwg) return false;
;         int wgid = (int)L; { const int q = nwg / NXCD, r = nwg % NXCD, xcd = wgid % NXCD, off = wgid / NXCD; wgid = (xcd < r ? xcd * (q + 1) : r * (q + 1) + (xcd - r) * q) + off; }
;         const int nig = WGM * nN, gid = wgid / nig, fm = gid * WGM, gsz = (nM - fm) < WGM ? (nM - fm) : WGM;
;         u.pm = fm + ((wgid % nig) % gsz); u.pn = (wgid % nig) / gsz; return true;
; __global__ void __launch_bounds__(NTHR, 2) mk_fwd(Params p) {
;     ...
;     if (IN(1)) {
;         pg8::Gemm g{ACTA, (const bf16_t*)(p.ws + WS_WGU1), T, 2 * FF, D}; pg8::StaticOrder S; S.init(T, 2 * FF, G, vc);
;         EpiSwiGLU<false> E{HID, nullptr};
;         pg8::gemm_phase<EpiSwiGLU<false>, pg8::StaticOrder, PG8_ALIGN, PG8_SP2>(lds, g, S, E);
.LBB0_398:
	s_load_dwordx2 s[2:3], s[88:89], 0xa0
	s_waitcnt lgkmcnt(0)
	s_cmp_lt_i32 s2, 4
	s_cselect_b64 s[2:3], -1, 0
	s_and_b64 s[22:23], s[2:3], s[0:1]
	s_andn2_b64 vcc, exec, s[22:23]
	s_cbranch_vccnz .LBB0_481
	s_mov_b32 s98, -1
	s_cmpk_lt_i32 s33, 0x840
	s_cselect_b64 s[0:1], -1, 0
	s_cmpk_gt_i32 s33, 0x83f
	v_readfirstlane_b32 s2, v198
	s_cbranch_scc1 .LBB0_401
	s_ashr_i32 s3, s33, 31
	s_lshr_b32 s3, s3, 29
	s_add_i32 s3, s33, s3
	s_ashr_i32 s4, s3, 3
	s_and_b32 s3, s3, -8
	s_sub_i32 s3, s33, s3
	s_cmp_lt_i32 s3, 0
	s_movk_i32 s5, 0x109
	s_cselect_b32 s5, s5, 0x108
	s_mul_i32 s3, s3, s5
	s_add_i32 s3, s3, s4
	s_mul_hi_i32 s4, s3, 0x2e8ba2e9
	s_lshr_b32 s5, s4, 31
	s_ashr_i32 s4, s4, 4
	s_add_i32 s4, s4, s5
	s_lshl_b32 s5, s4, 3
	s_mulk_i32 s4, 0x58
	s_sub_i32 s3, s3, s4
	s_bfe_i32 s4, s3, 0x80000
	s_bfe_u32 s4, s4, 0x3000c
	s_add_i32 s4, s3, s4
	s_bfe_i32 s6, s4, 0x80000
	s_and_b32 s4, s4, 0xf8
	s_sub_i32 s3, s3, s4
	s_sext_i32_i16 s6, s6
	s_sext_i32_i8 s3, s3
	s_add_i32 s4, s5, s3
	s_ashr_i32 s12, s6, 3

; __device__ __forceinline__ void row_rstd8(const float* ssq, int row0, int fq, float (&r)[8]) {
;     f32x4 pp[8];
; #pragma unroll
;     for (int q = 0; q < 8; ++q) pp[q] = *(const f32x4*)(ssq + (size_t)(row0 + (q >> 2) * 128 + (q & 3) * 16) * 16 + 4 * fq);
; #pragma unroll
;     for (int q = 0; q < 8; ++q) { float s = (pp[q][0] + pp[q][1]) + (pp[q][2] + pp[q][3]); s += __shfl_xor(s, 16); s += __shfl_xor(s, 32); r[q] = __builtin_amdgcn_rsqf(s * (1.0f / 1024.0f) + EPS); }
; }
;     __device__ __forceinline__ void operator()(const f32x4 (&acc)[2][2][4][2], const pg8::Unit& u, int wr, int wc, int fr, int fq) const {
;     ...
;                 const int row = row0 + ai * 128 + m * 16; const float pos = (float)row_pos(row);
;                 const float r = rr[ai * 4 + m];
; #pragma unroll
;                 for (int bj = 0; bj < 2; ++bj) {
;                     const int seg = 2 * u.pn + bj;
;                     float sc = r; if (seg < 4) sc = r * 0.125f; if (seg >= 10 && seg < 14) sc = r * 0.08838834764831845f;
;                     f32x4 v0 = acc[ai][bj][m][0] * sc, v1 = acc[ai][bj][m][1] * sc;
;                     const bool rotA = (seg <= 4) && ((wc & 1) == 0) && (fq < 2), rotR = (seg >= 6 && seg < 14);
;                     if (seg <= 4 || rotR) {
.LBB0_413:
	s_cmp_eq_u32 s4, s98
	s_cbranch_scc1 .Lg3_hit
	s_mov_b32 s98, s4
	v_lshl_add_u32 v148, s4, 8, v164
	v_or_b32_e32 v160, 16, v148
	v_ashrrev_i32_e32 v149, 31, v148
	v_ashrrev_i32_e32 v161, 31, v160
	v_lshlrev_b64 v[146:147], 6, v[148:149]
	v_lshlrev_b64 v[150:151], 6, v[160:161]
	v_or_b32_e32 v158, 32, v148
	v_or_b32_e32 v156, 48, v148
	v_lshl_add_u64 v[146:147], v[136:137], 0, v[146:147]
	v_lshl_add_u64 v[150:151], v[136:137], 0, v[150:151]
	v_ashrrev_i32_e32 v159, 31, v158
	v_ashrrev_i32_e32 v157, 31, v156
	global_load_dwordx4 v[188:191], v[146:147], off
	global_load_dwordx4 v[192:195], v[150:151], off
	v_lshlrev_b64 v[146:147], 6, v[158:159]
	v_lshlrev_b64 v[150:151], 6, v[156:157]
	v_add_u32_e32 v154, 0x80, v148
	v_add_u32_e32 v152, 0x90, v148
	v_lshl_add_u64 v[146:147], v[136:137], 0, v[146:147]
	v_lshl_add_u64 v[150:151], v[136:137], 0, v[150:151]
	v_ashrrev_i32_e32 v155, 31, v154
	v_ashrrev_i32_e32 v153, 31, v152
	global_load_dwordx4 v[200:203], v[146:147], off
	global_load_dwordx4 v[204:207], v[150:151], off
	v_lshlrev_b64 v[146:147], 6, v[154:155]
	v_lshlrev_b64 v[150:151], 6, v[152:153]
	v_lshl_add_u64 v[146:147], v[136:137], 0, v[146:147]
	v_lshl_add_u64 v[150:151], v[136:137], 0, v[150:151]
	global_load_dwordx4 v[208:211], v[146:147], off
	global_load_dwordx4 v[212:215], v[150:151], off
	v_add_u32_e32 v150, 0xa0, v148
	v_ashrrev_i32_e32 v151, 31, v150
	v_lshlrev_b64 v[146:147], 6, v[150:151]
	v_lshl_add_u64 v[146:147], v[136:137], 0, v[146:147]
	global_load_dwordx4 v[216:219], v[146:147], off
	v_add_u32_e32 v146, 0xb0, v148
	v_ashrrev_i32_e32 v147, 31, v146
	v_lshlrev_b64 v[162:163], 6, v[146:147]
	v_lshl_add_u64 v[162:163], v[136:137], 0, v[162:163]
	global_load_dwordx4 v[220:223], v[162:163], off
	v_and_b32_e32 v149, 64, v178
	v_xor_b32_e32 v147, 16, v178
	v_add_u32_e32 v149, 64, v149
	v_xor_b32_e32 v151, 32, v178
	v_cmp_lt_i32_e32 vcc, v147, v149
	s_lshl_b32 s18, s12, 1
	s_cmp_lt_i32 s12, 2
	v_cndmask_b32_e32 v147, v178, v147, vcc
	v_cmp_lt_i32_e32 vcc, v151, v149
	v_lshlrev_b32_e32 v147, 2, v147
	s_cselect_b64 s[8:9], -1, 0
	v_cndmask_b32_e32 v149, v178, v151, vcc
	v_lshlrev_b32_e32 v149, 2, v149
	s_add_i32 s4, s18, -10
	s_cmp_lt_u32 s4, 4
	s_cselect_b64 s[10:11], -1, 0
	s_cmp_lt_i32 s12, 3
	s_cselect_b64 s[42:43], -1, 0
	s_add_i32 s4, s18, -6
	s_cmp_lt_u32 s4, 8
	s_cselect_b64 s[4:5], -1, 0
	s_or_b64 s[16:17], s[42:43], s[4:5]
	v_cmp_gt_i32_e64 s[6:7], s61, v148
	s_mov_b64 s[14:15], -1
	s_and_b64 vcc, exec, s[16:17]
	s_waitcnt vmcnt(0)
	v_mov_b32_e32 v162, v189
	v_mov_b32_e32 v163, v190
	v_mov_b32_e32 v189, v191
	v_pk_add_f32 v[162:163], v[162:163], v[188:189]
	v_add_f32_e32 v151, v192, v193
	v_add_f32_e32 v153, v194, v195
	v_add_f32_e32 v162, v162, v163
	v_add_f32_e32 v151, v151, v153
	v_add_f32_e32 v155, v200, v201
	v_add_f32_e32 v157, v202, v203
	v_add_f32_e32 v153, v155, v157
	v_add_f32_e32 v159, v204, v205
	v_add_f32_e32 v161, v206, v207
	v_add_f32_e32 v188, v208, v209
	v_add_f32_e32 v189, v210, v211
	v_add_f32_e32 v157, v188, v189
	ds_bpermute_b32 v188, v147, v162
	ds_bpermute_b32 v189, v147, v151
	v_add_f32_e32 v190, v212, v213
	v_add_f32_e32 v191, v214, v215
	v_add_f32_e32 v192, v216, v217
	s_waitcnt lgkmcnt(1)
	v_add_f32_e32 v162, v162, v188
	s_waitcnt lgkmcnt(0)
	v_add_f32_e32 v196, v151, v189
	ds_bpermute_b32 v151, v149, v162
	v_add_f32_e32 v193, v218, v219
	v_add_f32_e32 v194, v220, v221
	v_add_f32_e32 v195, v222, v223
	v_add_f32_e32 v155, v159, v161
	v_add_f32_e32 v159, v190, v191
	v_add_f32_e32 v161, v192, v193
	v_add_f32_e32 v163, v194, v195
	ds_bpermute_b32 v190, v147, v153
	ds_bpermute_b32 v191, v147, v155
	ds_bpermute_b32 v193, v147, v157
	ds_bpermute_b32 v195, v147, v159
	ds_bpermute_b32 v197, v147, v161
	ds_bpermute_b32 v147, v147, v163
	s_waitcnt lgkmcnt(6)
	v_add_f32_e32 v151, v162, v151
	v_fmamk_f32 v151, v151, 0x3a800000, v179
	v_rsq_f32_e32 v200, v151
	s_waitcnt lgkmcnt(5)
	v_add_f32_e32 v194, v153, v190
	s_waitcnt lgkmcnt(4)
	v_add_f32_e32 v192, v155, v191
	s_waitcnt lgkmcnt(3)
	v_add_f32_e32 v190, v157, v193
	s_waitcnt lgkmcnt(2)
	v_add_f32_e32 v188, v159, v195
	s_waitcnt lgkmcnt(1)
	v_add_f32_e32 v159, v161, v197
	s_waitcnt lgkmcnt(0)
	v_add_f32_e32 v155, v163, v147
	ds_bpermute_b32 v197, v149, v196
	ds_bpermute_b32 v195, v149, v194
	ds_bpermute_b32 v193, v149, v192
	ds_bpermute_b32 v191, v149, v190
	ds_bpermute_b32 v189, v149, v188
	ds_bpermute_b32 v161, v149, v159
	ds_bpermute_b32 v157, v149, v155
	s_waitcnt lgkmcnt(0)
	v_mov_b32_e32 v248, v200
	v_add_f32_e32 v249, v196, v197
	v_fmamk_f32 v249, v249, 0x3a800000, v179
	v_rsq_f32_e32 v249, v249
	v_add_f32_e32 v250, v194, v195
	v_fmamk_f32 v250, v250, 0x3a800000, v179
	v_rsq_f32_e32 v250, v250
	v_add_f32_e32 v251, v192, v193
	v_fmamk_f32 v251, v251, 0x3a800000, v179
	v_rsq_f32_e32 v251, v251
	v_add_f32_e32 v252, v190, v191
	v_fmamk_f32 v252, v252, 0x3a800000, v179
	v_rsq_f32_e32 v252, v252
	v_add_f32_e32 v253, v188, v189
	v_fmamk_f32 v253, v253, 0x3a800000, v179
	v_rsq_f32_e32 v253, v253
	v_add_f32_e32 v254, v159, v161
	v_fmamk_f32 v254, v254, 0x3a800000, v179
	v_rsq_f32_e32 v254, v254
	v_add_f32_e32 v255, v155, v157
	v_fmamk_f32 v255, v255, 0x3a800000, v179
	v_rsq_f32_e32 v255, v255
	s_nop 0
.Lg3_common:
	v_mul_f32_e32 v202, 0x3e000000, v200
	v_mul_f32_e32 v201, 0x3db504f3, v200
	v_cndmask_b32_e64 v147, v200, v202, s[8:9]
	v_cndmask_b32_e64 v162, v147, v201, s[10:11]
	v_pk_mul_f32 v[126:127], v[126:127], v[162:163] op_sel_hi:[1,0]
	v_pk_mul_f32 v[124:125], v[124:125], v[162:163] op_sel_hi:[1,0]
	v_pk_mul_f32 v[122:123], v[122:123], v[162:163] op_sel_hi:[1,0]
	v_pk_mul_f32 v[162:163], v[120:121], v[162:163] op_sel_hi:[1,0]
	s_cbranch_vccnz .LBB0_415
	s_mov_b64 s[14:15], 0

; __device__ __forceinline__ unsigned cvt_pk_bf16(float lo, float hi) { unsigned r; asm volatile("v_cvt_pk_bf16_f32 %0, %1, %2" : "=v"(r) : "v"(lo), "v"(hi)); return r; }
; __device__ __forceinline__ unsigned cvt_pk_bf16(float lo, float hi) { f32x2_t v = {lo, hi}; bf16x2_t b = __builtin_convertvector(v, bf16x2_t); return __builtin_bit_cast(unsigned, b); }
;     __device__ __forceinline__ void operator()(const f32x4 (&acc)[2][2][4][2], const pg8::Unit& u, int wr, int wc, int fr, int fq) const {
;     ...
;             for (int m = 0; m < 4; ++m) {
;                 const int row = row0 + ai * 128 + m * 16; const float pos = (float)row_pos(row);
;                 const float r = rr[ai * 4 + m];
; #pragma unroll
;                 for (int bj = 0; bj < 2; ++bj) {
;                     const int seg = 2 * u.pn + bj;
;                     float sc = r; if (seg < 4) sc = r * 0.125f; if (seg >= 10 && seg < 14) sc = r * 0.08838834764831845f;
;                     f32x4 v0 = acc[ai][bj][m][0] * sc, v1 = acc[ai][bj][m][1] * sc;
;                     const bool rotA = (seg <= 4) && ((wc & 1) == 0) && (fq < 2), rotR = (seg >= 6 && seg < 14);
;                     if (seg <= 4 || rotR) {
; #pragma unroll
;                         for (int j = 0; j < 4; ++j) { const float rev = pos * (rotR ? fr4[j] : fa[j]), fv = rev - __builtin_floorf(rev);
;                             const float c = (rotA || rotR) ? __builtin_amdgcn_cosf(fv) : 1.0f, sn = (rotA || rotR) ? __builtin_amdgcn_sinf(fv) : 0.0f;
;                             const float x1 = v0[j], x2 = v1[j]; v0[j] = x1 * c - x2 * sn; v1[j] = x2 * c + x1 * sn; }
;                     }
;                     u32x4 w; w.x = cvt_pk_bf16(v0[0], v0[1]); w.y = cvt_pk_bf16(v0[2], v0[3]); w.z = cvt_pk_bf16(v1[0], v1[1]); w.w = cvt_pk_bf16(v1[2], v1[3]);
;                     *(u32x4*)(O + (size_t)row * DIN + col0 + bj * 128) = w;
.LBB0_421:
	v_mov_b32_e32 v162, v249
	v_cvt_pk_bf16_f32 v116, v116, v117
	v_cvt_pk_bf16_f32 v117, v118, v119
	v_cvt_pk_bf16_f32 v118, v112, v113
	v_mul_f32_e32 v113, 0x3e000000, v162
	v_cvt_pk_bf16_f32 v119, v114, v115
	v_mul_f32_e32 v114, 0x3db504f3, v162
	v_cndmask_b32_e64 v112, v162, v113, s[8:9]
	v_cndmask_b32_e64 v112, v112, v114, s[10:11]
	s_xor_b64 s[52:53], s[16:17], -1
	v_pk_mul_f32 v[110:111], v[110:111], v[112:113] op_sel_hi:[1,0]
	v_pk_mul_f32 v[108:109], v[108:109], v[112:113] op_sel_hi:[1,0]
	v_pk_mul_f32 v[106:107], v[106:107], v[112:113] op_sel_hi:[1,0]
	v_pk_mul_f32 v[104:105], v[104:105], v[112:113] op_sel_hi:[1,0]
	v_cndmask_b32_e64 v112, 0, 1, s[52:53]
	v_cmp_gt_i32_e64 s[18:19], s61, v160
	v_cmp_ne_u32_e64 s[16:17], 1, v112
	s_andn2_b64 vcc, exec, s[52:53]
	s_mov_b64 s[52:53], -1
	global_store_dwordx4 v[122:123], v[116:119], off offset:256
	s_cbranch_vccnz .LBB0_423
	s_mov_b64 s[52:53], 0

; __device__ __forceinline__ unsigned cvt_pk_bf16(float lo, float hi) { unsigned r; asm volatile("v_cvt_pk_bf16_f32 %0, %1, %2" : "=v"(r) : "v"(lo), "v"(hi)); return r; }
; __device__ __forceinline__ unsigned cvt_pk_bf16(float lo, float hi) { f32x2_t v = {lo, hi}; bf16x2_t b = __builtin_convertvector(v, bf16x2_t); return __builtin_bit_cast(unsigned, b); }
;     __device__ __forceinline__ void operator()(const f32x4 (&acc)[2][2][4][2], const pg8::Unit& u, int wr, int wc, int fr, int fq) const {
;     ...
;             for (int m = 0; m < 4; ++m) {
;                 const int row = row0 + ai * 128 + m * 16; const float pos = (float)row_pos(row);
;                 const float r = rr[ai * 4 + m];
; #pragma unroll
;                 for (int bj = 0; bj < 2; ++bj) {
;                     const int seg = 2 * u.pn + bj;
;                     float sc = r; if (seg < 4) sc = r * 0.125f; if (seg >= 10 && seg < 14) sc = r * 0.08838834764831845f;
;                     f32x4 v0 = acc[ai][bj][m][0] * sc, v1 = acc[ai][bj][m][1] * sc;
;                     const bool rotA = (seg <= 4) && ((wc & 1) == 0) && (fq < 2), rotR = (seg >= 6 && seg < 14);
;                     if (seg <= 4 || rotR) {
; #pragma unroll
;                         for (int j = 0; j < 4; ++j) { const float rev = pos * (rotR ? fr4[j] : fa[j]), fv = rev - __builtin_floorf(rev);
;                             const float c = (rotA || rotR) ? __builtin_amdgcn_cosf(fv) : 1.0f, sn = (rotA || rotR) ? __builtin_amdgcn_sinf(fv) : 0.0f;
;                             const float x1 = v0[j], x2 = v1[j]; v0[j] = x1 * c - x2 * sn; v1[j] = x2 * c + x1 * sn; }
;                     }
;                     u32x4 w; w.x = cvt_pk_bf16(v0[0], v0[1]); w.y = cvt_pk_bf16(v0[2], v0[3]); w.z = cvt_pk_bf16(v1[0], v1[1]); w.w = cvt_pk_bf16(v1[2], v1[3]);
;                     *(u32x4*)(O + (size_t)row * DIN + col0 + bj * 128) = w;
.LBB0_429:
	v_mov_b32_e32 v106, v250
	v_cvt_pk_bf16_f32 v100, v100, v101
	v_cvt_pk_bf16_f32 v101, v102, v103
	v_cvt_pk_bf16_f32 v102, v96, v97
	v_mul_f32_e32 v97, 0x3e000000, v106
	v_cvt_pk_bf16_f32 v103, v98, v99
	v_mul_f32_e32 v98, 0x3db504f3, v106
	v_cndmask_b32_e64 v96, v106, v97, s[8:9]
	v_cndmask_b32_e64 v96, v96, v98, s[10:11]
	v_cmp_gt_i32_e64 s[20:21], s61, v158
	v_pk_mul_f32 v[94:95], v[94:95], v[96:97] op_sel_hi:[1,0]
	v_pk_mul_f32 v[92:93], v[92:93], v[96:97] op_sel_hi:[1,0]
	v_pk_mul_f32 v[90:91], v[90:91], v[96:97] op_sel_hi:[1,0]
	v_pk_mul_f32 v[88:89], v[88:89], v[96:97] op_sel_hi:[1,0]
	s_and_b64 vcc, exec, s[16:17]
	s_mov_b64 s[52:53], -1
	global_store_dwordx4 v[104:105], v[100:103], off offset:256
	s_cbranch_vccnz .LBB0_431
	s_mov_b64 s[52:53], 0

; __device__ __forceinline__ unsigned cvt_pk_bf16(float lo, float hi) { unsigned r; asm volatile("v_cvt_pk_bf16_f32 %0, %1, %2" : "=v"(r) : "v"(lo), "v"(hi)); return r; }
; __device__ __forceinline__ unsigned cvt_pk_bf16(float lo, float hi) { f32x2_t v = {lo, hi}; bf16x2_t b = __builtin_convertvector(v, bf16x2_t); return __builtin_bit_cast(unsigned, b); }
;     __device__ __forceinline__ void operator()(const f32x4 (&acc)[2][2][4][2], const pg8::Unit& u, int wr, int wc, int fr, int fq) const {
;     ...
;             for (int m = 0; m < 4; ++m) {
;                 const int row = row0 + ai * 128 + m * 16; const float pos = (float)row_pos(row);
;                 const float r = rr[ai * 4 + m];
; #pragma unroll
;                 for (int bj = 0; bj < 2; ++bj) {
;                     const int seg = 2 * u.pn + bj;
;                     float sc = r; if (seg < 4) sc = r * 0.125f; if (seg >= 10 && seg < 14) sc = r * 0.08838834764831845f;
;                     f32x4 v0 = acc[ai][bj][m][0] * sc, v1 = acc[ai][bj][m][1] * sc;
;                     const bool rotA = (seg <= 4) && ((wc & 1) == 0) && (fq < 2), rotR = (seg >= 6 && seg < 14);
;                     if (seg <= 4 || rotR) {
; #pragma unroll
;                         for (int j = 0; j < 4; ++j) { const float rev = pos * (rotR ? fr4[j] : fa[j]), fv = rev - __builtin_floorf(rev);
;                             const float c = (rotA || rotR) ? __builtin_amdgcn_cosf(fv) : 1.0f, sn = (rotA || rotR) ? __builtin_amdgcn_sinf(fv) : 0.0f;
;                             const float x1 = v0[j], x2 = v1[j]; v0[j] = x1 * c - x2 * sn; v1[j] = x2 * c + x1 * sn; }
;                     }
;                     u32x4 w; w.x = cvt_pk_bf16(v0[0], v0[1]); w.y = cvt_pk_bf16(v0[2], v0[3]); w.z = cvt_pk_bf16(v1[0], v1[1]); w.w = cvt_pk_bf16(v1[2], v1[3]);
;                     *(u32x4*)(O + (size_t)row * DIN + col0 + bj * 128) = w;
.LBB0_437:
	v_mov_b32_e32 v90, v251
	v_cvt_pk_bf16_f32 v84, v84, v85
	v_cvt_pk_bf16_f32 v85, v86, v87
	v_cvt_pk_bf16_f32 v86, v80, v81
	v_mul_f32_e32 v81, 0x3e000000, v90
	v_cvt_pk_bf16_f32 v87, v82, v83
	v_mul_f32_e32 v82, 0x3db504f3, v90
	v_cndmask_b32_e64 v80, v90, v81, s[8:9]
	v_cndmask_b32_e64 v80, v80, v82, s[10:11]
	v_cmp_gt_i32_e64 s[20:21], s61, v156
	v_pk_mul_f32 v[78:79], v[78:79], v[80:81] op_sel_hi:[1,0]
	v_pk_mul_f32 v[76:77], v[76:77], v[80:81] op_sel_hi:[1,0]
	v_pk_mul_f32 v[74:75], v[74:75], v[80:81] op_sel_hi:[1,0]
	v_pk_mul_f32 v[72:73], v[72:73], v[80:81] op_sel_hi:[1,0]
	s_and_b64 vcc, exec, s[16:17]
	s_mov_b64 s[52:53], -1
	global_store_dwordx4 v[88:89], v[84:87], off offset:256
	s_cbranch_vccnz .LBB0_439
	s_mov_b64 s[52:53], 0

; __device__ __forceinline__ unsigned cvt_pk_bf16(float lo, float hi) { unsigned r; asm volatile("v_cvt_pk_bf16_f32 %0, %1, %2" : "=v"(r) : "v"(lo), "v"(hi)); return r; }
; __device__ __forceinline__ unsigned cvt_pk_bf16(float lo, float hi) { f32x2_t v = {lo, hi}; bf16x2_t b = __builtin_convertvector(v, bf16x2_t); return __builtin_bit_cast(unsigned, b); }
;     __device__ __forceinline__ void operator()(const f32x4 (&acc)[2][2][4][2], const pg8::Unit& u, int wr, int wc, int fr, int fq) const {
;     ...
;             for (int m = 0; m < 4; ++m) {
;                 const int row = row0 + ai * 128 + m * 16; const float pos = (float)row_pos(row);
;                 const float r = rr[ai * 4 + m];
; #pragma unroll
;                 for (int bj = 0; bj < 2; ++bj) {
;                     const int seg = 2 * u.pn + bj;
;                     float sc = r; if (seg < 4) sc = r * 0.125f; if (seg >= 10 && seg < 14) sc = r * 0.08838834764831845f;
;                     f32x4 v0 = acc[ai][bj][m][0] * sc, v1 = acc[ai][bj][m][1] * sc;
;                     const bool rotA = (seg <= 4) && ((wc & 1) == 0) && (fq < 2), rotR = (seg >= 6 && seg < 14);
;                     if (seg <= 4 || rotR) {
; #pragma unroll
;                         for (int j = 0; j < 4; ++j) { const float rev = pos * (rotR ? fr4[j] : fa[j]), fv = rev - __builtin_floorf(rev);
;                             const float c = (rotA || rotR) ? __builtin_amdgcn_cosf(fv) : 1.0f, sn = (rotA || rotR) ? __builtin_amdgcn_sinf(fv) : 0.0f;
;                             const float x1 = v0[j], x2 = v1[j]; v0[j] = x1 * c - x2 * sn; v1[j] = x2 * c + x1 * sn; }
;                     }
;                     u32x4 w; w.x = cvt_pk_bf16(v0[0], v0[1]); w.y = cvt_pk_bf16(v0[2], v0[3]); w.z = cvt_pk_bf16(v1[0], v1[1]); w.w = cvt_pk_bf16(v1[2], v1[3]);
;                     *(u32x4*)(O + (size_t)row * DIN + col0 + bj * 128) = w;
.LBB0_445:
	v_mov_b32_e32 v74, v252
	v_cvt_pk_bf16_f32 v68, v68, v69
	v_cvt_pk_bf16_f32 v69, v70, v71
	v_cvt_pk_bf16_f32 v70, v64, v65
	v_mul_f32_e32 v65, 0x3e000000, v74
	v_cvt_pk_bf16_f32 v71, v66, v67
	v_mul_f32_e32 v66, 0x3db504f3, v74
	v_cndmask_b32_e64 v64, v74, v65, s[8:9]
	v_cndmask_b32_e64 v64, v64, v66, s[10:11]
	v_cmp_gt_i32_e64 s[20:21], s72, v148
	v_pk_mul_f32 v[62:63], v[62:63], v[64:65] op_sel_hi:[1,0]
	v_pk_mul_f32 v[60:61], v[60:61], v[64:65] op_sel_hi:[1,0]
	v_pk_mul_f32 v[58:59], v[58:59], v[64:65] op_sel_hi:[1,0]
	v_pk_mul_f32 v[56:57], v[56:57], v[64:65] op_sel_hi:[1,0]
	s_and_b64 vcc, exec, s[16:17]
	s_mov_b64 s[52:53], -1
	global_store_dwordx4 v[72:73], v[68:71], off offset:256
	s_cbranch_vccnz .LBB0_447
	s_mov_b64 s[52:53], 0

; __device__ __forceinline__ unsigned cvt_pk_bf16(float lo, float hi) { unsigned r; asm volatile("v_cvt_pk_bf16_f32 %0, %1, %2" : "=v"(r) : "v"(lo), "v"(hi)); return r; }
; __device__ __forceinline__ unsigned cvt_pk_bf16(float lo, float hi) { f32x2_t v = {lo, hi}; bf16x2_t b = __builtin_convertvector(v, bf16x2_t); return __builtin_bit_cast(unsigned, b); }
;     __device__ __forceinline__ void operator()(const f32x4 (&acc)[2][2][4][2], const pg8::Unit& u, int wr, int wc, int fr, int fq) const {
;     ...
;             for (int m = 0; m < 4; ++m) {
;                 const int row = row0 + ai * 128 + m * 16; const float pos = (float)row_pos(row);
;                 const float r = rr[ai * 4 + m];
; #pragma unroll
;                 for (int bj = 0; bj < 2; ++bj) {
;                     const int seg = 2 * u.pn + bj;
;                     float sc = r; if (seg < 4) sc = r * 0.125f; if (seg >= 10 && seg < 14) sc = r * 0.08838834764831845f;
;                     f32x4 v0 = acc[ai][bj][m][0] * sc, v1 = acc[ai][bj][m][1] * sc;
;                     const bool rotA = (seg <= 4) && ((wc & 1) == 0) && (fq < 2), rotR = (seg >= 6 && seg < 14);
;                     if (seg <= 4 || rotR) {
; #pragma unroll
;                         for (int j = 0; j < 4; ++j) { const float rev = pos * (rotR ? fr4[j] : fa[j]), fv = rev - __builtin_floorf(rev);
;                             const float c = (rotA || rotR) ? __builtin_amdgcn_cosf(fv) : 1.0f, sn = (rotA || rotR) ? __builtin_amdgcn_sinf(fv) : 0.0f;
;                             const float x1 = v0[j], x2 = v1[j]; v0[j] = x1 * c - x2 * sn; v1[j] = x2 * c + x1 * sn; }
;                     }
;                     u32x4 w; w.x = cvt_pk_bf16(v0[0], v0[1]); w.y = cvt_pk_bf16(v0[2], v0[3]); w.z = cvt_pk_bf16(v1[0], v1[1]); w.w = cvt_pk_bf16(v1[2], v1[3]);
;                     *(u32x4*)(O + (size_t)row * DIN + col0 + bj * 128) = w;
.LBB0_453:
	v_mov_b32_e32 v58, v253
	v_cvt_pk_bf16_f32 v52, v52, v53
	v_cvt_pk_bf16_f32 v53, v54, v55
	v_cvt_pk_bf16_f32 v54, v48, v49
	v_mul_f32_e32 v49, 0x3e000000, v58
	v_cvt_pk_bf16_f32 v55, v50, v51
	v_mul_f32_e32 v50, 0x3db504f3, v58
	v_cndmask_b32_e64 v48, v58, v49, s[8:9]
	v_cndmask_b32_e64 v48, v48, v50, s[10:11]
	v_cmp_gt_i32_e64 s[20:21], s73, v148
	v_pk_mul_f32 v[46:47], v[46:47], v[48:49] op_sel_hi:[1,0]
	v_pk_mul_f32 v[44:45], v[44:45], v[48:49] op_sel_hi:[1,0]
	v_pk_mul_f32 v[42:43], v[42:43], v[48:49] op_sel_hi:[1,0]
	v_pk_mul_f32 v[40:41], v[40:41], v[48:49] op_sel_hi:[1,0]
	s_and_b64 vcc, exec, s[16:17]
	s_mov_b64 s[52:53], -1
	global_store_dwordx4 v[56:57], v[52:55], off offset:256
	s_cbranch_vccnz .LBB0_455
	s_mov_b64 s[52:53], 0

; __device__ __forceinline__ unsigned cvt_pk_bf16(float lo, float hi) { unsigned r; asm volatile("v_cvt_pk_bf16_f32 %0, %1, %2" : "=v"(r) : "v"(lo), "v"(hi)); return r; }
; __device__ __forceinline__ unsigned cvt_pk_bf16(float lo, float hi) { f32x2_t v = {lo, hi}; bf16x2_t b = __builtin_convertvector(v, bf16x2_t); return __builtin_bit_cast(unsigned, b); }
;     __device__ __forceinline__ void operator()(const f32x4 (&acc)[2][2][4][2], const pg8::Unit& u, int wr, int wc, int fr, int fq) const {
;     ...
;             for (int m = 0; m < 4; ++m) {
;                 const int row = row0 + ai * 128 + m * 16; const float pos = (float)row_pos(row);
;                 const float r = rr[ai * 4 + m];
; #pragma unroll
;                 for (int bj = 0; bj < 2; ++bj) {
;                     const int seg = 2 * u.pn + bj;
;                     float sc = r; if (seg < 4) sc = r * 0.125f; if (seg >= 10 && seg < 14) sc = r * 0.08838834764831845f;
;                     f32x4 v0 = acc[ai][bj][m][0] * sc, v1 = acc[ai][bj][m][1] * sc;
;                     const bool rotA = (seg <= 4) && ((wc & 1) == 0) && (fq < 2), rotR = (seg >= 6 && seg < 14);
;                     if (seg <= 4 || rotR) {
; #pragma unroll
;                         for (int j = 0; j < 4; ++j) { const float rev = pos * (rotR ? fr4[j] : fa[j]), fv = rev - __builtin_floorf(rev);
;                             const float c = (rotA || rotR) ? __builtin_amdgcn_cosf(fv) : 1.0f, sn = (rotA || rotR) ? __builtin_amdgcn_sinf(fv) : 0.0f;
;                             const float x1 = v0[j], x2 = v1[j]; v0[j] = x1 * c - x2 * sn; v1[j] = x2 * c + x1 * sn; }
;                     }
;                     u32x4 w; w.x = cvt_pk_bf16(v0[0], v0[1]); w.y = cvt_pk_bf16(v0[2], v0[3]); w.z = cvt_pk_bf16(v1[0], v1[1]); w.w = cvt_pk_bf16(v1[2], v1[3]);
;                     *(u32x4*)(O + (size_t)row * DIN + col0 + bj * 128) = w;
.LBB0_461:
	v_mov_b32_e32 v42, v254
	v_cvt_pk_bf16_f32 v36, v36, v37
	v_cvt_pk_bf16_f32 v37, v38, v39
	v_cvt_pk_bf16_f32 v38, v32, v33
	v_mul_f32_e32 v33, 0x3e000000, v42
	v_cvt_pk_bf16_f32 v39, v34, v35
	v_mul_f32_e32 v34, 0x3db504f3, v42
	v_cndmask_b32_e64 v32, v42, v33, s[8:9]
	v_cndmask_b32_e64 v32, v32, v34, s[10:11]
	v_cmp_gt_i32_e64 s[20:21], s74, v148
	v_pk_mul_f32 v[30:31], v[30:31], v[32:33] op_sel_hi:[1,0]
	v_pk_mul_f32 v[28:29], v[28:29], v[32:33] op_sel_hi:[1,0]
	v_pk_mul_f32 v[26:27], v[26:27], v[32:33] op_sel_hi:[1,0]
	v_pk_mul_f32 v[24:25], v[24:25], v[32:33] op_sel_hi:[1,0]
	s_and_b64 vcc, exec, s[16:17]
	s_mov_b64 s[52:53], -1
	global_store_dwordx4 v[40:41], v[36:39], off offset:256
	s_cbranch_vccnz .LBB0_463
	s_mov_b64 s[52:53], 0

; __device__ __forceinline__ unsigned cvt_pk_bf16(float lo, float hi) { unsigned r; asm volatile("v_cvt_pk_bf16_f32 %0, %1, %2" : "=v"(r) : "v"(lo), "v"(hi)); return r; }
; __device__ __forceinline__ unsigned cvt_pk_bf16(float lo, float hi) { f32x2_t v = {lo, hi}; bf16x2_t b = __builtin_convertvector(v, bf16x2_t); return __builtin_bit_cast(unsigned, b); }
;     __device__ __forceinline__ void operator()(const f32x4 (&acc)[2][2][4][2], const pg8::Unit& u, int wr, int wc, int fr, int fq) const {
;     ...
;             for (int m = 0; m < 4; ++m) {
;                 const int row = row0 + ai * 128 + m * 16; const float pos = (float)row_pos(row);
;                 const float r = rr[ai * 4 + m];
; #pragma unroll
;                 for (int bj = 0; bj < 2; ++bj) {
;                     const int seg = 2 * u.pn + bj;
;                     float sc = r; if (seg < 4) sc = r * 0.125f; if (seg >= 10 && seg < 14) sc = r * 0.08838834764831845f;
;                     f32x4 v0 = acc[ai][bj][m][0] * sc, v1 = acc[ai][bj][m][1] * sc;
;                     const bool rotA = (seg <= 4) && ((wc & 1) == 0) && (fq < 2), rotR = (seg >= 6 && seg < 14);
;                     if (seg <= 4 || rotR) {
; #pragma unroll
;                         for (int j = 0; j < 4; ++j) { const float rev = pos * (rotR ? fr4[j] : fa[j]), fv = rev - __builtin_floorf(rev);
;                             const float c = (rotA || rotR) ? __builtin_amdgcn_cosf(fv) : 1.0f, sn = (rotA || rotR) ? __builtin_amdgcn_sinf(fv) : 0.0f;
;                             const float x1 = v0[j], x2 = v1[j]; v0[j] = x1 * c - x2 * sn; v1[j] = x2 * c + x1 * sn; }
;                     }
;                     u32x4 w; w.x = cvt_pk_bf16(v0[0], v0[1]); w.y = cvt_pk_bf16(v0[2], v0[3]); w.z = cvt_pk_bf16(v1[0], v1[1]); w.w = cvt_pk_bf16(v1[2], v1[3]);
;                     *(u32x4*)(O + (size_t)row * DIN + col0 + bj * 128) = w;
.LBB0_469:
	v_mov_b32_e32 v26, v255
	v_cvt_pk_bf16_f32 v20, v20, v21
	v_cvt_pk_bf16_f32 v21, v22, v23
	v_cvt_pk_bf16_f32 v22, v16, v17
	v_mul_f32_e32 v17, 0x3e000000, v26
	v_cvt_pk_bf16_f32 v23, v18, v19
	v_mul_f32_e32 v18, 0x3db504f3, v26
	v_cndmask_b32_e64 v16, v26, v17, s[8:9]
	v_cndmask_b32_e64 v16, v16, v18, s[10:11]
	v_cmp_gt_i32_e64 s[20:21], s75, v148
	v_pk_mul_f32 v[14:15], v[14:15], v[16:17] op_sel_hi:[1,0]
	v_pk_mul_f32 v[12:13], v[12:13], v[16:17] op_sel_hi:[1,0]
	v_pk_mul_f32 v[10:11], v[10:11], v[16:17] op_sel_hi:[1,0]
	v_pk_mul_f32 v[8:9], v[8:9], v[16:17] op_sel_hi:[1,0]
	s_and_b64 vcc, exec, s[16:17]
	s_mov_b64 s[8:9], -1
	global_store_dwordx4 v[24:25], v[20:23], off offset:256
	s_cbranch_vccnz .LBB0_471
	s_mov_b64 s[8:9], 0

;     __device__ __forceinline__ void operator()(const f32x4 (&acc)[2][2][4][2], const pg8::Unit& u, int wr, int wc, int fr, int fq) const {
;         const int row0 = u.pm * 256 + wr * 64 + fr, col0 = u.pn * 256 + wc * 32 + 8 * fq;
;         float rr[8]; row_rstd8(ssq, row0, fq, rr);
;         float fa[4], fr4[4];
; #pragma unroll
;         for (int j = 0; j < 4; ++j) { fa[j] = 0.15915494309189535f * exp2f(-18.931568569324174f * ((float)(2 * (4 * fq + j)) * (1.0f / 16.0f)));
;                                       fr4[j] = 0.15915494309189535f * exp2f(-13.287712379549449f * ((float)(16 * wc + 4 * fq + j) * (1.0f / 63.0f))); }
; #pragma unroll
;         for (int ai = 0; ai < 2; ++ai)
; #pragma unroll
;             for (int m = 0; m < 4; ++m) {
;                 const int row = row0 + ai * 128 + m * 16; const float pos = (float)row_pos(row);
;                 const float r = rr[ai * 4 + m];
; #pragma unroll
;                 for (int bj = 0; bj < 2; ++bj) {
;                     const int seg = 2 * u.pn + bj;
;                     float sc = r; if (seg < 4) sc = r * 0.125f; if (seg >= 10 && seg < 14) sc = r * 0.08838834764831845f;
;                     f32x4 v0 = acc[ai][bj][m][0] * sc, v1 = acc[ai][bj][m][1] * sc;
;                     const bool rotA = (seg <= 4) && ((wc & 1) == 0) && (fq < 2), rotR = (seg >= 6 && seg < 14);
.Lg3_hit:
	v_lshl_add_u32 v148, s4, 8, v164
	v_or_b32_e32 v160, 16, v148
	v_ashrrev_i32_e32 v149, 31, v148
	v_ashrrev_i32_e32 v161, 31, v160
	v_lshlrev_b64 v[146:147], 6, v[148:149]
	v_lshlrev_b64 v[150:151], 6, v[160:161]
	v_or_b32_e32 v158, 32, v148
	v_or_b32_e32 v156, 48, v148
	v_lshl_add_u64 v[146:147], v[136:137], 0, v[146:147]
	v_lshl_add_u64 v[150:151], v[136:137], 0, v[150:151]
	v_ashrrev_i32_e32 v159, 31, v158
	v_ashrrev_i32_e32 v157, 31, v156
	v_lshlrev_b64 v[146:147], 6, v[158:159]
	v_lshlrev_b64 v[150:151], 6, v[156:157]
	v_add_u32_e32 v154, 0x80, v148
	v_add_u32_e32 v152, 0x90, v148
	v_lshl_add_u64 v[146:147], v[136:137], 0, v[146:147]
	v_lshl_add_u64 v[150:151], v[136:137], 0, v[150:151]
	v_ashrrev_i32_e32 v155, 31, v154
	v_ashrrev_i32_e32 v153, 31, v152
	v_lshlrev_b64 v[146:147], 6, v[154:155]
	v_lshlrev_b64 v[150:151], 6, v[152:153]
	v_lshl_add_u64 v[146:147], v[136:137], 0, v[146:147]
	v_lshl_add_u64 v[150:151], v[136:137], 0, v[150:151]
	v_add_u32_e32 v150, 0xa0, v148
	v_ashrrev_i32_e32 v151, 31, v150
	v_lshlrev_b64 v[146:147], 6, v[150:151]
	v_lshl_add_u64 v[146:147], v[136:137], 0, v[146:147]
	v_add_u32_e32 v146, 0xb0, v148
	v_ashrrev_i32_e32 v147, 31, v146
	v_lshlrev_b64 v[162:163], 6, v[146:147]
	v_lshl_add_u64 v[162:163], v[136:137], 0, v[162:163]
	v_and_b32_e32 v149, 64, v178
	v_xor_b32_e32 v147, 16, v178
	v_add_u32_e32 v149, 64, v149
	v_xor_b32_e32 v151, 32, v178
	v_cmp_lt_i32_e32 vcc, v147, v149
	s_lshl_b32 s18, s12, 1
	s_cmp_lt_i32 s12, 2
	v_cndmask_b32_e32 v147, v178, v147, vcc
	v_cmp_lt_i32_e32 vcc, v151, v149
	v_lshlrev_b32_e32 v147, 2, v147
	s_cselect_b64 s[8:9], -1, 0
	v_cndmask_b32_e32 v149, v178, v151, vcc
	v_lshlrev_b32_e32 v149, 2, v149
	s_add_i32 s4, s18, -10
	s_cmp_lt_u32 s4, 4
	s_cselect_b64 s[10:11], -1, 0
	s_cmp_lt_i32 s12, 3
	s_cselect_b64 s[42:43], -1, 0
	s_add_i32 s4, s18, -6
	s_cmp_lt_u32 s4, 8
	s_cselect_b64 s[4:5], -1, 0
	s_or_b64 s[16:17], s[42:43], s[4:5]
	v_cmp_gt_i32_e64 s[6:7], s61, v148
	s_mov_b64 s[14:15], -1
	s_and_b64 vcc, exec, s[16:17]
	v_mov_b32_e32 v200, v248
	s_branch .Lg3_common
